# attn loop: mid-PV barrier moved one MFMA later so the last V fragment reads have an MFMA of slack before the lgkmcnt(0)+barrier
# baseline (speedup 1.0000x reference)
; __device__ __forceinline__ void partialSM(f32x16& p0, f32x16& p1, float& m_reg, float& mn, float& alpha) {
;     ...
;   for (int r = 0; r < 16; ++r) p0[r] = fmaf(p0[r], C, mnC);
; #pragma unroll
;   for (int r = 0; r < 16; ++r) p1[r] = fmaf(p1[r], C, mnC);
; #pragma unroll
;   for (int r = 0; r < 16; ++r) p0[r] = __builtin_amdgcn_exp2f(p0[r]);
; }
; __device__ __forceinline__ void finishSM(f32x16& p0, f32x16& p1, float alpha, float& l_reg, bf16x8& pa0, bf16x8& pa1, bf16x8& pa2, bf16x8& pa3) {
; #pragma unroll
;   for (int r = 0; r < 16; ++r) p1[r] = __builtin_amdgcn_exp2f(p1[r]);
;   float ps = 0;
; #pragma unroll
;   for (int r = 0; r < 16; ++r) ps += p0[r];
; #pragma unroll
;   for (int r = 0; r < 16; ++r) ps += p1[r];
;   { auto rr = __builtin_amdgcn_permlane32_swap(__float_as_uint(ps), __float_as_uint(ps), false, false);
;     ps = __uint_as_float(rr[0]) + __uint_as_float(rr[1]); }
;   l_reg = l_reg * alpha + ps;
;     ...
;   PK4(p0, 0, pa0); PK4(p0, 8, pa1); PK4(p1, 0, pa2); PK4(p1, 8, pa3);
;     ...
; }
; __device__ __forceinline__ void qkt(f32x16& p0, f32x16& p1, const char* Ks, const bf16x8* qr, const char* qrl, int r32, int hi) {
;   p0 = f32x16{}; p1 = f32x16{};
; #pragma unroll
;   for (int d0 = 0; d0 < 8; ++d0) { int cb = (d0 * 16 + hi * 8) * 2;
;     bf16x8 b0 = *reinterpret_cast<const bf16x8*>(Ks + KSWZ(r32, cb));
;     bf16x8 b1 = *reinterpret_cast<const bf16x8*>(Ks + KSWZ(32 + r32, cb));
;     p0 = __builtin_amdgcn_mfma_f32_32x32x16_bf16(b0, qr[d0], p0, 0, 0, 0);
;     p1 = __builtin_amdgcn_mfma_f32_32x32x16_bf16(b1, qr[d0], p1, 0, 0, 0); }
; #pragma unroll
;   for (int d0 = 8; d0 < 12; ++d0) { int cb = (d0 * 16 + hi * 8) * 2;
;     bf16x8 b0 = *reinterpret_cast<const bf16x8*>(Ks + KSWZ(r32, cb));
;     bf16x8 b1 = *reinterpret_cast<const bf16x8*>(Ks + KSWZ(32 + r32, cb));
;     bf16x8 qf = *reinterpret_cast<const bf16x8*>(qrl + (((2 * (d0 - 8) + hi) ^ ((r32 >> 1) & 7)) << 4));
;     p0 = __builtin_amdgcn_mfma_f32_32x32x16_bf16(b0, qf, p0, 0, 0, 0);
;     p1 = __builtin_amdgcn_mfma_f32_32x32x16_bf16(b1, qf, p1, 0, 0, 0); }
; }
; __device__ __forceinline__ int v_st(int k, int c) { const int kk = (k & ~0xC) | ((k & 4) << 1) | ((k & 8) >> 1); return ((kk >> 3) * 4 + (c >> 5)) * 512 + ((kk & 7) * 32 + (c & 31)) * 2; }
.Lattn_join1p:
	v_mul_f32_e32 v194, 0xbdd53b94, v210
	v_fmamk_f32 v225, v80, 0x3dd53b94, v194
	v_fmamk_f32 v228, v81, 0x3dd53b94, v194
	s_waitcnt lgkmcnt(4)
	v_mfma_f32_32x32x16_bf16 v[16:31], v[152:155], v[240:243], v[16:31]
	ds_read_b64_tr_b16 v[240:241], v180 offset:9216
	ds_read_b64_tr_b16 v[242:243], v180 offset:11264
	v_fmamk_f32 v226, v82, 0x3dd53b94, v194
	v_fmamk_f32 v229, v83, 0x3dd53b94, v194
	v_fmamk_f32 v150, v76, 0x3dd53b94, v194
	v_fmamk_f32 v151, v77, 0x3dd53b94, v194
	v_fmamk_f32 v148, v78, 0x3dd53b94, v194
	v_fmamk_f32 v149, v79, 0x3dd53b94, v194
	v_mfma_f32_32x32x16_bf16 v[0:15], v[152:155], v[248:251], v[0:15]
	ds_read_b64_tr_b16 v[248:249], v180 offset:9728
	ds_read_b64_tr_b16 v[250:251], v180 offset:11776
	v_fmamk_f32 v227, v84, 0x3dd53b94, v194
	v_fmamk_f32 v230, v85, 0x3dd53b94, v194
	v_fmamk_f32 v223, v86, 0x3dd53b94, v194
	v_fmamk_f32 v224, v87, 0x3dd53b94, v194
	v_fmamk_f32 v154, v72, 0x3dd53b94, v194
	v_fmamk_f32 v155, v73, 0x3dd53b94, v194
	s_waitcnt lgkmcnt(4)
	v_mfma_f32_32x32x16_bf16 v[32:47], v[156:159], v[232:235], v[32:47]
	ds_read_b64_tr_b16 v[232:233], v180 offset:12288
	ds_read_b64_tr_b16 v[234:235], v180 offset:14336
	v_fmamk_f32 v152, v74, 0x3dd53b94, v194
	v_fmamk_f32 v153, v75, 0x3dd53b94, v194
	v_fmamk_f32 v219, v88, 0x3dd53b94, v194
	v_fmamk_f32 v221, v89, 0x3dd53b94, v194
	v_fmamk_f32 v220, v90, 0x3dd53b94, v194
	v_fmamk_f32 v222, v91, 0x3dd53b94, v194
	v_mfma_f32_32x32x16_bf16 v[48:63], v[156:159], v[236:239], v[48:63]
	ds_read_b64_tr_b16 v[236:237], v180 offset:12800
	ds_read_b64_tr_b16 v[238:239], v180 offset:14848
	s_waitcnt lgkmcnt(4)
	v_mfma_f32_32x32x16_bf16 v[16:31], v[156:159], v[240:243], v[16:31]
	ds_read_b64_tr_b16 v[240:241], v180 offset:13312
	ds_read_b64_tr_b16 v[242:243], v180 offset:15360
	v_mfma_f32_32x32x16_bf16 v[0:15], v[156:159], v[248:251], v[0:15]
	ds_read_b64_tr_b16 v[248:249], v180 offset:13824
	ds_read_b64_tr_b16 v[250:251], v180 offset:15872
	v_fmamk_f32 v158, v68, 0x3dd53b94, v194
	v_fmamk_f32 v159, v69, 0x3dd53b94, v194
	v_fmamk_f32 v156, v70, 0x3dd53b94, v194
	v_fmamk_f32 v157, v71, 0x3dd53b94, v194
	v_fmamk_f32 v215, v92, 0x3dd53b94, v194
	v_fmamk_f32 v217, v93, 0x3dd53b94, v194
	s_waitcnt lgkmcnt(4)
	v_mfma_f32_32x32x16_bf16 v[32:47], v[160:163], v[232:235], v[32:47]
	v_fmamk_f32 v216, v94, 0x3dd53b94, v194
	v_fmamk_f32 v218, v95, 0x3dd53b94, v194
	s_waitcnt lgkmcnt(0)
	s_barrier
	ds_read_b128 v[232:235], v199 offset:12288
	v_mfma_f32_32x32x16_bf16 v[48:63], v[160:163], v[236:239], v[48:63]
	ds_read_b128 v[236:239], v199 offset:24576
	v_mfma_f32_32x32x16_bf16 v[16:31], v[160:163], v[240:243], v[16:31]
	ds_read_b128 v[240:243], v205 offset:12288
	v_mfma_f32_32x32x16_bf16 v[0:15], v[160:163], v[248:251], v[0:15]
	ds_read_b128 v[248:251], v205 offset:24576
	v_fmamk_f32 v162, v64, 0x3dd53b94, v194
	v_fmamk_f32 v163, v65, 0x3dd53b94, v194
	v_fmamk_f32 v160, v66, 0x3dd53b94, v194
	v_fmamk_f32 v161, v67, 0x3dd53b94, v194
	s_and_b64 vcc, exec, s[40:41]
	s_cbranch_vccnz .Lattn_skip_rs1p
	s_and_saveexec_b64 s[18:19], s[38:39]
	ds_write_b32 v175, v214 offset:128
	s_or_b64 exec, exec, s[18:19]
	s_waitcnt lgkmcnt(0)
	v_add_u32_e32 v194, v173, v164
	ds_read_b128 v[64:67], v194 offset:224
	ds_read_b128 v[68:71], v194 offset:192
	ds_read_b128 v[72:75], v194 offset:160
	ds_read_b128 v[76:79], v194 offset:128
	s_waitcnt lgkmcnt(0)
	v_pk_mul_f32 v[44:45], v[44:45], v[64:65]
	v_pk_mul_f32 v[46:47], v[46:47], v[66:67]
	v_pk_mul_f32 v[40:41], v[40:41], v[68:69]
	v_pk_mul_f32 v[42:43], v[42:43], v[70:71]
	v_pk_mul_f32 v[36:37], v[36:37], v[72:73]
	v_pk_mul_f32 v[38:39], v[38:39], v[74:75]
	v_pk_mul_f32 v[32:33], v[32:33], v[76:77]
	v_pk_mul_f32 v[34:35], v[34:35], v[78:79]
	v_pk_mul_f32 v[60:61], v[60:61], v[64:65]
	v_pk_mul_f32 v[62:63], v[62:63], v[66:67]
	v_pk_mul_f32 v[56:57], v[56:57], v[68:69]
	v_pk_mul_f32 v[58:59], v[58:59], v[70:71]
	v_pk_mul_f32 v[52:53], v[52:53], v[72:73]
	v_pk_mul_f32 v[54:55], v[54:55], v[74:75]
	v_pk_mul_f32 v[48:49], v[48:49], v[76:77]
	v_pk_mul_f32 v[50:51], v[50:51], v[78:79]
	v_pk_mul_f32 v[28:29], v[28:29], v[64:65]
	v_pk_mul_f32 v[30:31], v[30:31], v[66:67]
	v_pk_mul_f32 v[24:25], v[24:25], v[68:69]
	v_pk_mul_f32 v[26:27], v[26:27], v[70:71]
	v_pk_mul_f32 v[20:21], v[20:21], v[72:73]
	v_pk_mul_f32 v[22:23], v[22:23], v[74:75]
	v_pk_mul_f32 v[16:17], v[16:17], v[76:77]
	v_pk_mul_f32 v[18:19], v[18:19], v[78:79]
	v_pk_mul_f32 v[12:13], v[12:13], v[64:65]
	v_pk_mul_f32 v[14:15], v[14:15], v[66:67]
	v_pk_mul_f32 v[8:9], v[8:9], v[68:69]
	v_pk_mul_f32 v[10:11], v[10:11], v[70:71]
	v_pk_mul_f32 v[4:5], v[4:5], v[72:73]
	v_pk_mul_f32 v[6:7], v[6:7], v[74:75]
	v_pk_mul_f32 v[0:1], v[0:1], v[76:77]
	v_pk_mul_f32 v[2:3], v[2:3], v[78:79]

; __device__ __forceinline__ void partialSM(f32x16& p0, f32x16& p1, float& m_reg, float& mn, float& alpha) {
;     ...
;   for (int r = 0; r < 16; ++r) p0[r] = fmaf(p0[r], C, mnC);
; #pragma unroll
;   for (int r = 0; r < 16; ++r) p1[r] = fmaf(p1[r], C, mnC);
; #pragma unroll
;   for (int r = 0; r < 16; ++r) p0[r] = __builtin_amdgcn_exp2f(p0[r]);
; }
; __device__ __forceinline__ void finishSM(f32x16& p0, f32x16& p1, float alpha, float& l_reg, bf16x8& pa0, bf16x8& pa1, bf16x8& pa2, bf16x8& pa3) {
; #pragma unroll
;   for (int r = 0; r < 16; ++r) p1[r] = __builtin_amdgcn_exp2f(p1[r]);
;   float ps = 0;
; #pragma unroll
;   for (int r = 0; r < 16; ++r) ps += p0[r];
; #pragma unroll
;   for (int r = 0; r < 16; ++r) ps += p1[r];
;   { auto rr = __builtin_amdgcn_permlane32_swap(__float_as_uint(ps), __float_as_uint(ps), false, false);
;     ps = __uint_as_float(rr[0]) + __uint_as_float(rr[1]); }
;   l_reg = l_reg * alpha + ps;
;     ...
;   PK4(p0, 0, pa0); PK4(p0, 8, pa1); PK4(p1, 0, pa2); PK4(p1, 8, pa3);
;     ...
; }
; __device__ __forceinline__ void qkt(f32x16& p0, f32x16& p1, const char* Ks, const bf16x8* qr, const char* qrl, int r32, int hi) {
;   p0 = f32x16{}; p1 = f32x16{};
; #pragma unroll
;   for (int d0 = 0; d0 < 8; ++d0) { int cb = (d0 * 16 + hi * 8) * 2;
;     bf16x8 b0 = *reinterpret_cast<const bf16x8*>(Ks + KSWZ(r32, cb));
;     bf16x8 b1 = *reinterpret_cast<const bf16x8*>(Ks + KSWZ(32 + r32, cb));
;     p0 = __builtin_amdgcn_mfma_f32_32x32x16_bf16(b0, qr[d0], p0, 0, 0, 0);
;     p1 = __builtin_amdgcn_mfma_f32_32x32x16_bf16(b1, qr[d0], p1, 0, 0, 0); }
; #pragma unroll
;   for (int d0 = 8; d0 < 12; ++d0) { int cb = (d0 * 16 + hi * 8) * 2;
;     bf16x8 b0 = *reinterpret_cast<const bf16x8*>(Ks + KSWZ(r32, cb));
;     bf16x8 b1 = *reinterpret_cast<const bf16x8*>(Ks + KSWZ(32 + r32, cb));
;     bf16x8 qf = *reinterpret_cast<const bf16x8*>(qrl + (((2 * (d0 - 8) + hi) ^ ((r32 >> 1) & 7)) << 4));
;     p0 = __builtin_amdgcn_mfma_f32_32x32x16_bf16(b0, qf, p0, 0, 0, 0);
;     p1 = __builtin_amdgcn_mfma_f32_32x32x16_bf16(b1, qf, p1, 0, 0, 0); }
; }
; __device__ __forceinline__ int v_st(int k, int c) { const int kk = (k & ~0xC) | ((k & 4) << 1) | ((k & 8) >> 1); return ((kk >> 3) * 4 + (c >> 5)) * 512 + ((kk & 7) * 32 + (c & 31)) * 2; }
.Lattn_join2p:
	v_mul_f32_e32 v194, 0xbdd53b94, v210
	s_sub_i32 s100, s30, 1
	s_cmp_eq_u32 s30, 0
	s_cselect_b32 s100, 2, s100
	s_add_i32 s101, s30, 1
	s_cmp_lg_u32 s30, 2
	s_cselect_b32 s101, s101, 0
	s_movk_i32 s34, 0x6000
	v_fmamk_f32 v225, v80, 0x3dd53b94, v194
	s_waitcnt lgkmcnt(4)
	v_mfma_f32_32x32x16_bf16 v[16:31], v[152:155], v[240:243], v[16:31]
	ds_read_b64_tr_b16 v[240:241], v231 offset:9216
	ds_read_b64_tr_b16 v[242:243], v231 offset:11264
	v_fmamk_f32 v228, v81, 0x3dd53b94, v194
	v_fmamk_f32 v226, v82, 0x3dd53b94, v194
	v_fmamk_f32 v229, v83, 0x3dd53b94, v194
	v_fmamk_f32 v150, v76, 0x3dd53b94, v194
	v_fmamk_f32 v151, v77, 0x3dd53b94, v194
	v_fmamk_f32 v148, v78, 0x3dd53b94, v194
	v_mfma_f32_32x32x16_bf16 v[0:15], v[152:155], v[248:251], v[0:15]
	ds_read_b64_tr_b16 v[248:249], v231 offset:9728
	ds_read_b64_tr_b16 v[250:251], v231 offset:11776
	v_fmamk_f32 v149, v79, 0x3dd53b94, v194
	v_fmamk_f32 v227, v84, 0x3dd53b94, v194
	v_fmamk_f32 v230, v85, 0x3dd53b94, v194
	v_fmamk_f32 v223, v86, 0x3dd53b94, v194
	v_fmamk_f32 v224, v87, 0x3dd53b94, v194
	v_fmamk_f32 v154, v72, 0x3dd53b94, v194
	s_waitcnt lgkmcnt(4)
	v_mfma_f32_32x32x16_bf16 v[32:47], v[156:159], v[232:235], v[32:47]
	ds_read_b64_tr_b16 v[232:233], v231 offset:12288
	ds_read_b64_tr_b16 v[234:235], v231 offset:14336
	v_fmamk_f32 v155, v73, 0x3dd53b94, v194
	v_fmamk_f32 v152, v74, 0x3dd53b94, v194
	v_fmamk_f32 v153, v75, 0x3dd53b94, v194
	v_fmamk_f32 v219, v88, 0x3dd53b94, v194
	v_fmamk_f32 v221, v89, 0x3dd53b94, v194
	v_fmamk_f32 v220, v90, 0x3dd53b94, v194
	v_mfma_f32_32x32x16_bf16 v[48:63], v[156:159], v[236:239], v[48:63]
	ds_read_b64_tr_b16 v[236:237], v231 offset:12800
	ds_read_b64_tr_b16 v[238:239], v231 offset:14848
	v_fmamk_f32 v222, v91, 0x3dd53b94, v194
	s_waitcnt lgkmcnt(4)
	v_mfma_f32_32x32x16_bf16 v[16:31], v[156:159], v[240:243], v[16:31]
	ds_read_b64_tr_b16 v[240:241], v231 offset:13312
	ds_read_b64_tr_b16 v[242:243], v231 offset:15360
	v_mfma_f32_32x32x16_bf16 v[0:15], v[156:159], v[248:251], v[0:15]
	ds_read_b64_tr_b16 v[248:249], v231 offset:13824
	ds_read_b64_tr_b16 v[250:251], v231 offset:15872
	v_fmamk_f32 v158, v68, 0x3dd53b94, v194
	v_fmamk_f32 v159, v69, 0x3dd53b94, v194
	v_fmamk_f32 v156, v70, 0x3dd53b94, v194
	v_fmamk_f32 v157, v71, 0x3dd53b94, v194
	v_fmamk_f32 v215, v92, 0x3dd53b94, v194
	v_fmamk_f32 v217, v93, 0x3dd53b94, v194
	s_waitcnt lgkmcnt(4)
	v_mfma_f32_32x32x16_bf16 v[32:47], v[160:163], v[232:235], v[32:47]
	v_fmamk_f32 v216, v94, 0x3dd53b94, v194
	v_fmamk_f32 v218, v95, 0x3dd53b94, v194
	s_waitcnt lgkmcnt(0)
	s_barrier
	ds_read_b128 v[232:235], v199 offset:36864
	v_mfma_f32_32x32x16_bf16 v[48:63], v[160:163], v[236:239], v[48:63]
	ds_read_b128 v[236:239], v199 offset:49152
	v_mfma_f32_32x32x16_bf16 v[16:31], v[160:163], v[240:243], v[16:31]
	ds_read_b128 v[240:243], v205 offset:36864
	v_mfma_f32_32x32x16_bf16 v[0:15], v[160:163], v[248:251], v[0:15]
	ds_read_b128 v[248:251], v205 offset:49152
	v_fmamk_f32 v162, v64, 0x3dd53b94, v194
	v_fmamk_f32 v163, v65, 0x3dd53b94, v194
	v_fmamk_f32 v160, v66, 0x3dd53b94, v194
	v_fmamk_f32 v161, v67, 0x3dd53b94, v194
	s_and_b64 vcc, exec, s[40:41]
	s_cbranch_vccnz .Lattn_skip_rs2p
	s_and_saveexec_b64 s[18:19], s[38:39]
	ds_write_b32 v175, v213 offset:128
	s_or_b64 exec, exec, s[18:19]
	s_waitcnt lgkmcnt(0)
	v_add_u32_e32 v194, v173, v164
	ds_read_b128 v[64:67], v194 offset:224
	ds_read_b128 v[68:71], v194 offset:192
	ds_read_b128 v[72:75], v194 offset:160
	ds_read_b128 v[76:79], v194 offset:128
	s_waitcnt lgkmcnt(0)
	v_pk_mul_f32 v[44:45], v[44:45], v[64:65]
	v_pk_mul_f32 v[46:47], v[46:47], v[66:67]
	v_pk_mul_f32 v[40:41], v[40:41], v[68:69]
	v_pk_mul_f32 v[42:43], v[42:43], v[70:71]
	v_pk_mul_f32 v[36:37], v[36:37], v[72:73]
	v_pk_mul_f32 v[38:39], v[38:39], v[74:75]
	v_pk_mul_f32 v[32:33], v[32:33], v[76:77]
	v_pk_mul_f32 v[34:35], v[34:35], v[78:79]
	v_pk_mul_f32 v[60:61], v[60:61], v[64:65]
	v_pk_mul_f32 v[62:63], v[62:63], v[66:67]
	v_pk_mul_f32 v[56:57], v[56:57], v[68:69]
	v_pk_mul_f32 v[58:59], v[58:59], v[70:71]
	v_pk_mul_f32 v[52:53], v[52:53], v[72:73]
	v_pk_mul_f32 v[54:55], v[54:55], v[74:75]
	v_pk_mul_f32 v[48:49], v[48:49], v[76:77]
	v_pk_mul_f32 v[50:51], v[50:51], v[78:79]
	v_pk_mul_f32 v[28:29], v[28:29], v[64:65]
	v_pk_mul_f32 v[30:31], v[30:31], v[66:67]
	v_pk_mul_f32 v[24:25], v[24:25], v[68:69]
	v_pk_mul_f32 v[26:27], v[26:27], v[70:71]
	v_pk_mul_f32 v[20:21], v[20:21], v[72:73]
	v_pk_mul_f32 v[22:23], v[22:23], v[74:75]
	v_pk_mul_f32 v[16:17], v[16:17], v[76:77]
	v_pk_mul_f32 v[18:19], v[18:19], v[78:79]
	v_pk_mul_f32 v[12:13], v[12:13], v[64:65]
	v_pk_mul_f32 v[14:15], v[14:15], v[66:67]
	v_pk_mul_f32 v[8:9], v[8:9], v[68:69]
	v_pk_mul_f32 v[10:11], v[10:11], v[70:71]
	v_pk_mul_f32 v[4:5], v[4:5], v[72:73]
	v_pk_mul_f32 v[6:7], v[6:7], v[74:75]
	v_pk_mul_f32 v[0:1], v[0:1], v[76:77]
	v_pk_mul_f32 v[2:3], v[2:3], v[78:79]
